# LDS-DMA K-loop now in all seven 128x128 GEMM phases incl. split-K ones; S2 scan units rebalanced across workgroups
# speedup vs baseline: 1.0519x; 1.0122x over previous
.LBB0_572:
	s_or_b64 exec, exec, s[0:1]
	s_add_u32 s8, s90, 0x38b0100
	s_addc_u32 s9, s91, 0
	s_add_u32 s78, s90, 0x37ea100
	s_addc_u32 s79, s91, 0
	s_cmpk_gt_i32 s33, 0x10ff
	s_waitcnt lgkmcnt(0)
	s_barrier
	s_cbranch_scc1 .LBB0_697
	v_and_b32_e32 v0, 8, v146
	v_lshlrev_b32_e32 v68, 2, v159
	v_mov_b32_e32 v69, 0
	v_lshlrev_b32_e32 v1, 2, v0
	s_movk_i32 s0, 0x44
	v_lshlrev_b32_e32 v2, 7, v147
	v_lshl_add_u64 v[70:71], s[2:3], 0, v[68:69]
	s_waitcnt vmcnt(1)
	v_mad_u32_u24 v118, v147, s0, v1
	v_lshlrev_b32_e32 v119, 7, v159
	v_mul_u32_u24_e32 v120, 0x44, v159
	s_mov_b32 s0, 0
	v_lshlrev_b32_e32 v72, 2, v2
	v_lshlrev_b32_e32 v74, 2, v0
	v_lshlrev_b32_e32 v76, 2, v128
	v_mov_b32_e32 v121, 0x8020000
	s_mov_b32 s16, s33
	s_movk_i32 s101, 0x700
	s_cmpk_lt_i32 s33, 0x100
	s_cbranch_scc1 .Ls2_init_done
	s_addk_i32 s16, 0x600
	s_movk_i32 s101, 0x1100
.Ls2_init_done:
	s_branch .LBB0_577

.LBB0_576:
	s_addk_i32 s16, 0x100
	s_cmp_lt_i32 s16, s101
	s_cbranch_scc0 .LBB0_697

.LBB0_1099:
	s_cmp_ge_i32 s65, s72
	s_cselect_b64 s[36:37], -1, 0
	s_sub_i32 s2, s65, s72
	s_and_b32 s3, 1, s2
	s_lshr_b32 s2, s2, 1
	s_add_i32 s2, s2, s72
	s_cmp_eq_u32 s3, 1
	s_cselect_b32 s3, 0x580, 0
	s_cmp_lt_i32 s65, s72
	s_cselect_b32 s2, s65, s2
	s_mul_hi_i32 s6, s2, 0x2aaaaaab
	s_cselect_b32 s8, 44, 22
	s_cselect_b32 s3, 0, s3
	s_lshr_b32 s7, s6, 31
	s_ashr_i32 s6, s6, 4
	s_add_i32 s6, s6, s7
	s_mul_i32 s7, s6, 0x60
	s_sub_i32 s2, s2, s7
	s_lshl_b32 s9, s2, 7
	s_lshl_b32 s24, s3, 1
	s_lshl_b32 s10, s6, 7
	v_lshl_or_b32 v64, v183, 3, v191
	v_and_b32_e32 v65, 63, v64
	v_lshrrev_b32_e32 v66, 3, v65
	v_lshrrev_b32_e32 v67, 4, v65
	v_xor_b32_e32 v67, v67, v65
	v_and_b32_e32 v67, 7, v67
	v_lshlrev_b32_e32 v67, 4, v67
	s_movk_i32 s99, 0x1600
	v_mad_u32_u24 v112, v66, s99, v67
	v_xor_b32_e32 v68, 64, v112
	v_add_u32_e32 v113, 0xac00, v68
	v_add_u32_e32 v114, 0x15800, v112
	v_add_u32_e32 v115, 0x20400, v68
	v_add_u32_e32 v116, 0x2c000, v112
	v_add_u32_e32 v117, 0x36c00, v68
	v_add_u32_e32 v118, 0x41800, v112
	v_add_u32_e32 v119, 0x4c400, v68
	v_and_b32_e32 v69, 31, v64
	v_bfe_u32 v70, v64, 5, 1
	v_bfe_u32 v71, v64, 1, 3
	v_xor_b32_e32 v71, v71, v70
	v_lshlrev_b32_e32 v71, 4, v71
	v_bfe_u32 v72, v64, 7, 1
	v_lshl_or_b32 v72, v72, 6, v69
	v_lshl_add_u32 v120, v72, 7, v71
	v_bfe_u32 v73, v64, 6, 1
	v_lshl_or_b32 v73, v73, 6, v69
	v_lshl_add_u32 v124, v73, 7, v71
	v_add_u32_e32 v124, 0x4000, v124
	v_xor_b32_e32 v121, 32, v120
	v_xor_b32_e32 v125, 32, v124
	v_xor_b32_e32 v122, 64, v120
	v_xor_b32_e32 v126, 64, v124
	v_xor_b32_e32 v123, 96, v120
	v_xor_b32_e32 v127, 96, v124
	v_lshrrev_b32_e32 v74, 6, v64
	s_nop 0
	v_readfirstlane_b32 s100, v74
	s_nop 3
	s_lshl_b32 s98, s100, 13
	s_mov_b32 s101, 0x2140000
	s_mov_b32 s99, s10
	s_cmp_lt_u32 s100, 2
	s_cmov_b32 s101, 0x3971900
	s_cmov_b32 s99, s9
	s_and_b32 s100, s100, 1
	s_lshl_b32 s100, s100, 6
	s_add_u32 s99, s99, s100
	s_mul_i32 s99, s99, 0x1600
	s_add_u32 s99, s99, s101
	s_add_u32 s99, s99, s24
	s_add_u32 s2, s90, s99
	s_addc_u32 s3, s91, 0
	s_add_u32 m0, s98, 0x0
	s_nop 0
	global_load_lds_dwordx4 v112, s[2:3] offset:0
	global_load_lds_dwordx4 v113, s[2:3] offset:1024
	global_load_lds_dwordx4 v114, s[2:3] offset:2048
	global_load_lds_dwordx4 v115, s[2:3] offset:3072
	s_add_u32 m0, s98, 0x1000
	s_nop 0
	global_load_lds_dwordx4 v116, s[2:3] offset:0
	global_load_lds_dwordx4 v117, s[2:3] offset:1024
	global_load_lds_dwordx4 v118, s[2:3] offset:2048
	global_load_lds_dwordx4 v119, s[2:3] offset:3072
	s_add_u32 s2, s2, 0x80
	s_addc_u32 s3, s3, 0
	s_add_u32 m0, s98, 0x8000
	s_nop 0
	global_load_lds_dwordx4 v112, s[2:3] offset:0
	global_load_lds_dwordx4 v113, s[2:3] offset:1024
	global_load_lds_dwordx4 v114, s[2:3] offset:2048
	global_load_lds_dwordx4 v115, s[2:3] offset:3072
	s_add_u32 m0, s98, 0x9000
	s_nop 0
	global_load_lds_dwordx4 v116, s[2:3] offset:0
	global_load_lds_dwordx4 v117, s[2:3] offset:1024
	global_load_lds_dwordx4 v118, s[2:3] offset:2048
	global_load_lds_dwordx4 v119, s[2:3] offset:3072
	s_add_u32 s2, s2, 0x80
	s_addc_u32 s3, s3, 0
	v_mov_b32_e32 v48, 0
	v_mov_b32_e32 v49, 0
	v_mov_b32_e32 v50, 0
	v_mov_b32_e32 v51, 0
	v_mov_b32_e32 v52, 0
	v_mov_b32_e32 v53, 0
	v_mov_b32_e32 v54, 0
	v_mov_b32_e32 v55, 0
	v_mov_b32_e32 v56, 0
	v_mov_b32_e32 v57, 0
	v_mov_b32_e32 v58, 0
	v_mov_b32_e32 v59, 0
	v_mov_b32_e32 v60, 0
	v_mov_b32_e32 v61, 0
	v_mov_b32_e32 v62, 0
	v_mov_b32_e32 v63, 0
	v_mov_b32_e32 v16, 0
	v_mov_b32_e32 v17, 0
	v_mov_b32_e32 v18, 0
	v_mov_b32_e32 v19, 0
	v_mov_b32_e32 v20, 0
	v_mov_b32_e32 v21, 0
	v_mov_b32_e32 v22, 0
	v_mov_b32_e32 v23, 0
	v_mov_b32_e32 v24, 0
	v_mov_b32_e32 v25, 0
	v_mov_b32_e32 v26, 0
	v_mov_b32_e32 v27, 0
	v_mov_b32_e32 v28, 0
	v_mov_b32_e32 v29, 0
	v_mov_b32_e32 v30, 0
	v_mov_b32_e32 v31, 0
	v_mov_b32_e32 v32, 0
	v_mov_b32_e32 v33, 0
	v_mov_b32_e32 v34, 0
	v_mov_b32_e32 v35, 0
	v_mov_b32_e32 v36, 0
	v_mov_b32_e32 v37, 0
	v_mov_b32_e32 v38, 0
	v_mov_b32_e32 v39, 0
	v_mov_b32_e32 v40, 0
	v_mov_b32_e32 v41, 0
	v_mov_b32_e32 v42, 0
	v_mov_b32_e32 v43, 0
	v_mov_b32_e32 v44, 0
	v_mov_b32_e32 v45, 0
	v_mov_b32_e32 v46, 0
	v_mov_b32_e32 v47, 0
	v_mov_b32_e32 v0, 0
	v_mov_b32_e32 v1, 0
	v_mov_b32_e32 v2, 0
	v_mov_b32_e32 v3, 0
	v_mov_b32_e32 v4, 0
	v_mov_b32_e32 v5, 0
	v_mov_b32_e32 v6, 0
	v_mov_b32_e32 v7, 0
	v_mov_b32_e32 v8, 0
	v_mov_b32_e32 v9, 0
	v_mov_b32_e32 v10, 0
	v_mov_b32_e32 v11, 0
	v_mov_b32_e32 v12, 0
	v_mov_b32_e32 v13, 0
	v_mov_b32_e32 v14, 0
	v_mov_b32_e32 v15, 0
	s_lshr_b32 s7, s8, 1
	s_sub_u32 s7, s7, 1
	s_waitcnt vmcnt(8)
.Lg3_loop:
	s_waitcnt vmcnt(8)
	s_barrier
	ds_read_b128 v[64:67], v120 offset:0
	ds_read_b128 v[72:75], v124 offset:0
	ds_read_b128 v[76:79], v124 offset:4096
	ds_read_b128 v[68:71], v120 offset:4096
	ds_read_b128 v[80:83], v121 offset:0
	ds_read_b128 v[88:91], v125 offset:0
	ds_read_b128 v[92:95], v125 offset:4096
	ds_read_b128 v[84:87], v121 offset:4096
	s_waitcnt lgkmcnt(4)
	v_mfma_f32_32x32x16_bf16 v[48:63], v[64:67], v[72:75], v[48:63]
	ds_read_b128 v[96:99], v122 offset:0
	v_mfma_f32_32x32x16_bf16 v[16:31], v[64:67], v[76:79], v[16:31]
	ds_read_b128 v[104:107], v126 offset:0
	v_mfma_f32_32x32x16_bf16 v[32:47], v[68:71], v[72:75], v[32:47]
	ds_read_b128 v[108:111], v126 offset:4096
	v_mfma_f32_32x32x16_bf16 v[0:15], v[68:71], v[76:79], v[0:15]
	ds_read_b128 v[100:103], v122 offset:4096
	s_waitcnt lgkmcnt(4)
	v_mfma_f32_32x32x16_bf16 v[48:63], v[80:83], v[88:91], v[48:63]
	ds_read_b128 v[64:67], v123 offset:0
	v_mfma_f32_32x32x16_bf16 v[16:31], v[80:83], v[92:95], v[16:31]
	ds_read_b128 v[72:75], v127 offset:0
	v_mfma_f32_32x32x16_bf16 v[32:47], v[84:87], v[88:91], v[32:47]
	ds_read_b128 v[76:79], v127 offset:4096
	v_mfma_f32_32x32x16_bf16 v[0:15], v[84:87], v[92:95], v[0:15]
	ds_read_b128 v[68:71], v123 offset:4096
	s_waitcnt lgkmcnt(4)
	v_mfma_f32_32x32x16_bf16 v[48:63], v[96:99], v[104:107], v[48:63]
	v_mfma_f32_32x32x16_bf16 v[16:31], v[96:99], v[108:111], v[16:31]
	v_mfma_f32_32x32x16_bf16 v[32:47], v[100:103], v[104:107], v[32:47]
	v_mfma_f32_32x32x16_bf16 v[0:15], v[100:103], v[108:111], v[0:15]
	s_waitcnt lgkmcnt(0)
	v_mfma_f32_32x32x16_bf16 v[48:63], v[64:67], v[72:75], v[48:63]
	v_mfma_f32_32x32x16_bf16 v[16:31], v[64:67], v[76:79], v[16:31]
	v_mfma_f32_32x32x16_bf16 v[32:47], v[68:71], v[72:75], v[32:47]
	v_mfma_f32_32x32x16_bf16 v[0:15], v[68:71], v[76:79], v[0:15]
	s_barrier
	s_add_u32 m0, s98, 0x0
	s_nop 0
	global_load_lds_dwordx4 v112, s[2:3] offset:0
	global_load_lds_dwordx4 v113, s[2:3] offset:1024
	global_load_lds_dwordx4 v114, s[2:3] offset:2048
	global_load_lds_dwordx4 v115, s[2:3] offset:3072
	s_add_u32 m0, s98, 0x1000
	s_nop 0
	global_load_lds_dwordx4 v116, s[2:3] offset:0
	global_load_lds_dwordx4 v117, s[2:3] offset:1024
	global_load_lds_dwordx4 v118, s[2:3] offset:2048
	global_load_lds_dwordx4 v119, s[2:3] offset:3072
	s_add_u32 s2, s2, 0x80
	s_addc_u32 s3, s3, 0
	s_waitcnt vmcnt(8)
	s_barrier
	ds_read_b128 v[64:67], v120 offset:32768
	ds_read_b128 v[72:75], v124 offset:32768
	ds_read_b128 v[76:79], v124 offset:36864
	ds_read_b128 v[68:71], v120 offset:36864
	ds_read_b128 v[80:83], v121 offset:32768
	ds_read_b128 v[88:91], v125 offset:32768
	ds_read_b128 v[92:95], v125 offset:36864
	ds_read_b128 v[84:87], v121 offset:36864
	s_waitcnt lgkmcnt(4)
	v_mfma_f32_32x32x16_bf16 v[48:63], v[64:67], v[72:75], v[48:63]
	ds_read_b128 v[96:99], v122 offset:32768
	v_mfma_f32_32x32x16_bf16 v[16:31], v[64:67], v[76:79], v[16:31]
	ds_read_b128 v[104:107], v126 offset:32768
	v_mfma_f32_32x32x16_bf16 v[32:47], v[68:71], v[72:75], v[32:47]
	ds_read_b128 v[108:111], v126 offset:36864
	v_mfma_f32_32x32x16_bf16 v[0:15], v[68:71], v[76:79], v[0:15]
	ds_read_b128 v[100:103], v122 offset:36864
	s_waitcnt lgkmcnt(4)
	v_mfma_f32_32x32x16_bf16 v[48:63], v[80:83], v[88:91], v[48:63]
	ds_read_b128 v[64:67], v123 offset:32768
	v_mfma_f32_32x32x16_bf16 v[16:31], v[80:83], v[92:95], v[16:31]
	ds_read_b128 v[72:75], v127 offset:32768
	v_mfma_f32_32x32x16_bf16 v[32:47], v[84:87], v[88:91], v[32:47]
	ds_read_b128 v[76:79], v127 offset:36864
	v_mfma_f32_32x32x16_bf16 v[0:15], v[84:87], v[92:95], v[0:15]
	ds_read_b128 v[68:71], v123 offset:36864
	s_waitcnt lgkmcnt(4)
	v_mfma_f32_32x32x16_bf16 v[48:63], v[96:99], v[104:107], v[48:63]
	v_mfma_f32_32x32x16_bf16 v[16:31], v[96:99], v[108:111], v[16:31]
	v_mfma_f32_32x32x16_bf16 v[32:47], v[100:103], v[104:107], v[32:47]
	v_mfma_f32_32x32x16_bf16 v[0:15], v[100:103], v[108:111], v[0:15]
	s_waitcnt lgkmcnt(0)
	v_mfma_f32_32x32x16_bf16 v[48:63], v[64:67], v[72:75], v[48:63]
	v_mfma_f32_32x32x16_bf16 v[16:31], v[64:67], v[76:79], v[16:31]
	v_mfma_f32_32x32x16_bf16 v[32:47], v[68:71], v[72:75], v[32:47]
	v_mfma_f32_32x32x16_bf16 v[0:15], v[68:71], v[76:79], v[0:15]
	s_barrier
	s_add_u32 m0, s98, 0x8000
	s_nop 0
	global_load_lds_dwordx4 v112, s[2:3] offset:0
	global_load_lds_dwordx4 v113, s[2:3] offset:1024
	global_load_lds_dwordx4 v114, s[2:3] offset:2048
	global_load_lds_dwordx4 v115, s[2:3] offset:3072
	s_add_u32 m0, s98, 0x9000
	s_nop 0
	global_load_lds_dwordx4 v116, s[2:3] offset:0
	global_load_lds_dwordx4 v117, s[2:3] offset:1024
	global_load_lds_dwordx4 v118, s[2:3] offset:2048
	global_load_lds_dwordx4 v119, s[2:3] offset:3072
	s_add_u32 s2, s2, 0x80
	s_addc_u32 s3, s3, 0
	s_sub_u32 s7, s7, 1
	s_cmp_lg_u32 s7, 0
	s_cbranch_scc1 .Lg3_loop
	s_waitcnt vmcnt(8)
	s_barrier
	ds_read_b128 v[64:67], v120 offset:0
	ds_read_b128 v[72:75], v124 offset:0
	ds_read_b128 v[76:79], v124 offset:4096
	ds_read_b128 v[68:71], v120 offset:4096
	ds_read_b128 v[80:83], v121 offset:0
	ds_read_b128 v[88:91], v125 offset:0
	ds_read_b128 v[92:95], v125 offset:4096
	ds_read_b128 v[84:87], v121 offset:4096
	s_waitcnt lgkmcnt(4)
	v_mfma_f32_32x32x16_bf16 v[48:63], v[64:67], v[72:75], v[48:63]
	ds_read_b128 v[96:99], v122 offset:0
	v_mfma_f32_32x32x16_bf16 v[16:31], v[64:67], v[76:79], v[16:31]
	ds_read_b128 v[104:107], v126 offset:0
	v_mfma_f32_32x32x16_bf16 v[32:47], v[68:71], v[72:75], v[32:47]
	ds_read_b128 v[108:111], v126 offset:4096
	v_mfma_f32_32x32x16_bf16 v[0:15], v[68:71], v[76:79], v[0:15]
	ds_read_b128 v[100:103], v122 offset:4096
	s_waitcnt lgkmcnt(4)
	v_mfma_f32_32x32x16_bf16 v[48:63], v[80:83], v[88:91], v[48:63]
	ds_read_b128 v[64:67], v123 offset:0
	v_mfma_f32_32x32x16_bf16 v[16:31], v[80:83], v[92:95], v[16:31]
	ds_read_b128 v[72:75], v127 offset:0
	v_mfma_f32_32x32x16_bf16 v[32:47], v[84:87], v[88:91], v[32:47]
	ds_read_b128 v[76:79], v127 offset:4096
	v_mfma_f32_32x32x16_bf16 v[0:15], v[84:87], v[92:95], v[0:15]
	ds_read_b128 v[68:71], v123 offset:4096
	s_waitcnt lgkmcnt(4)
	v_mfma_f32_32x32x16_bf16 v[48:63], v[96:99], v[104:107], v[48:63]
	v_mfma_f32_32x32x16_bf16 v[16:31], v[96:99], v[108:111], v[16:31]
	v_mfma_f32_32x32x16_bf16 v[32:47], v[100:103], v[104:107], v[32:47]
	v_mfma_f32_32x32x16_bf16 v[0:15], v[100:103], v[108:111], v[0:15]
	s_waitcnt lgkmcnt(0)
	v_mfma_f32_32x32x16_bf16 v[48:63], v[64:67], v[72:75], v[48:63]
	v_mfma_f32_32x32x16_bf16 v[16:31], v[64:67], v[76:79], v[16:31]
	v_mfma_f32_32x32x16_bf16 v[32:47], v[68:71], v[72:75], v[32:47]
	v_mfma_f32_32x32x16_bf16 v[0:15], v[68:71], v[76:79], v[0:15]
	s_barrier
	s_waitcnt vmcnt(0)
	s_barrier
	ds_read_b128 v[64:67], v120 offset:32768
	ds_read_b128 v[72:75], v124 offset:32768
	ds_read_b128 v[76:79], v124 offset:36864
	ds_read_b128 v[68:71], v120 offset:36864
	ds_read_b128 v[80:83], v121 offset:32768
	ds_read_b128 v[88:91], v125 offset:32768
	ds_read_b128 v[92:95], v125 offset:36864
	ds_read_b128 v[84:87], v121 offset:36864
	s_waitcnt lgkmcnt(4)
	v_mfma_f32_32x32x16_bf16 v[48:63], v[64:67], v[72:75], v[48:63]
	ds_read_b128 v[96:99], v122 offset:32768
	v_mfma_f32_32x32x16_bf16 v[16:31], v[64:67], v[76:79], v[16:31]
	ds_read_b128 v[104:107], v126 offset:32768
	v_mfma_f32_32x32x16_bf16 v[32:47], v[68:71], v[72:75], v[32:47]
	ds_read_b128 v[108:111], v126 offset:36864
	v_mfma_f32_32x32x16_bf16 v[0:15], v[68:71], v[76:79], v[0:15]
	ds_read_b128 v[100:103], v122 offset:36864
	s_waitcnt lgkmcnt(4)
	v_mfma_f32_32x32x16_bf16 v[48:63], v[80:83], v[88:91], v[48:63]
	ds_read_b128 v[64:67], v123 offset:32768
	v_mfma_f32_32x32x16_bf16 v[16:31], v[80:83], v[92:95], v[16:31]
	ds_read_b128 v[72:75], v127 offset:32768
	v_mfma_f32_32x32x16_bf16 v[32:47], v[84:87], v[88:91], v[32:47]
	ds_read_b128 v[76:79], v127 offset:36864
	v_mfma_f32_32x32x16_bf16 v[0:15], v[84:87], v[92:95], v[0:15]
	ds_read_b128 v[68:71], v123 offset:36864
	s_waitcnt lgkmcnt(4)
	v_mfma_f32_32x32x16_bf16 v[48:63], v[96:99], v[104:107], v[48:63]
	v_mfma_f32_32x32x16_bf16 v[16:31], v[96:99], v[108:111], v[16:31]
	v_mfma_f32_32x32x16_bf16 v[32:47], v[100:103], v[104:107], v[32:47]
	v_mfma_f32_32x32x16_bf16 v[0:15], v[100:103], v[108:111], v[0:15]
	s_waitcnt lgkmcnt(0)
	v_mfma_f32_32x32x16_bf16 v[48:63], v[64:67], v[72:75], v[48:63]
	v_mfma_f32_32x32x16_bf16 v[16:31], v[64:67], v[76:79], v[16:31]
	v_mfma_f32_32x32x16_bf16 v[32:47], v[68:71], v[72:75], v[32:47]
	v_mfma_f32_32x32x16_bf16 v[0:15], v[68:71], v[76:79], v[0:15]
	s_nop 7
	s_nop 7
	s_branch .LBB0_1107

.LBB0_1874:
	s_cmp_ge_i32 s55, s72
	s_cselect_b64 s[36:37], -1, 0
	s_sub_i32 s4, s55, s72
	s_and_b32 s5, 1, s4
	s_lshr_b32 s4, s4, 1
	s_add_i32 s4, s4, s72
	s_cmp_eq_u32 s5, 1
	s_cselect_b32 s5, 0x200, 0
	s_cmp_lt_i32 s55, s72
	s_cselect_b32 s4, s55, s4
	s_mul_hi_i32 s6, s4, 0x2aaaaaab
	s_cselect_b32 s8, 16, 8
	s_cselect_b32 s5, 0, s5
	s_lshr_b32 s7, s6, 31
	s_ashr_i32 s6, s6, 4
	s_add_i32 s6, s6, s7
	s_mul_i32 s7, s6, 0x60
	s_sub_i32 s4, s4, s7
	s_lshl_b32 s9, s4, 7
	s_lshl_b32 s10, s6, 7
	s_lshl_b32 s26, s5, 1
	v_lshl_or_b32 v64, v183, 3, v191
	v_and_b32_e32 v65, 63, v64
	v_lshrrev_b32_e32 v66, 3, v65
	v_lshrrev_b32_e32 v67, 4, v65
	v_xor_b32_e32 v67, v67, v65
	v_and_b32_e32 v67, 7, v67
	v_lshlrev_b32_e32 v67, 4, v67
	s_movk_i32 s99, 0x800
	v_mad_u32_u24 v112, v66, s99, v67
	v_xor_b32_e32 v68, 64, v112
	v_add_u32_e32 v113, 0x3c00, v68
	v_add_u32_e32 v114, 0x7800, v112
	v_add_u32_e32 v115, 0xb400, v68
	v_add_u32_e32 v116, 0x10000, v112
	v_add_u32_e32 v117, 0x13c00, v68
	v_add_u32_e32 v118, 0x17800, v112
	v_add_u32_e32 v119, 0x1b400, v68
	v_and_b32_e32 v69, 31, v64
	v_bfe_u32 v70, v64, 5, 1
	v_bfe_u32 v71, v64, 1, 3
	v_xor_b32_e32 v71, v71, v70
	v_lshlrev_b32_e32 v71, 4, v71
	v_bfe_u32 v72, v64, 7, 1
	v_lshl_or_b32 v72, v72, 6, v69
	v_lshl_add_u32 v120, v72, 7, v71
	v_bfe_u32 v73, v64, 6, 1
	v_lshl_or_b32 v73, v73, 6, v69
	v_lshl_add_u32 v124, v73, 7, v71
	v_add_u32_e32 v124, 0x4000, v124
	v_xor_b32_e32 v121, 32, v120
	v_xor_b32_e32 v125, 32, v124
	v_xor_b32_e32 v122, 64, v120
	v_xor_b32_e32 v126, 64, v124
	v_xor_b32_e32 v123, 96, v120
	v_xor_b32_e32 v127, 96, v124
	v_lshrrev_b32_e32 v74, 6, v64
	s_nop 0
	v_readfirstlane_b32 s100, v74
	s_nop 3
	s_lshl_b32 s98, s100, 13
	s_mov_b32 s101, 0x3240000
	s_mov_b32 s99, s10
	s_cmp_lt_u32 s100, 2
	s_cmov_b32 s101, 0xc971900
	s_cmov_b32 s99, s9
	s_and_b32 s100, s100, 1
	s_lshl_b32 s100, s100, 6
	s_add_u32 s99, s99, s100
	s_mul_i32 s99, s99, 0x800
	s_add_u32 s99, s99, s101
	s_add_u32 s99, s99, s26
	s_add_u32 s4, s90, s99
	s_addc_u32 s5, s91, 0
	s_add_u32 m0, s98, 0x0
	s_nop 0
	global_load_lds_dwordx4 v112, s[4:5] offset:0
	global_load_lds_dwordx4 v113, s[4:5] offset:1024
	global_load_lds_dwordx4 v114, s[4:5] offset:2048
	global_load_lds_dwordx4 v115, s[4:5] offset:3072
	s_add_u32 m0, s98, 0x1000
	s_nop 0
	global_load_lds_dwordx4 v116, s[4:5] offset:0
	global_load_lds_dwordx4 v117, s[4:5] offset:1024
	global_load_lds_dwordx4 v118, s[4:5] offset:2048
	global_load_lds_dwordx4 v119, s[4:5] offset:3072
	s_add_u32 s4, s4, 0x80
	s_addc_u32 s5, s5, 0
	s_add_u32 m0, s98, 0x8000
	s_nop 0
	global_load_lds_dwordx4 v112, s[4:5] offset:0
	global_load_lds_dwordx4 v113, s[4:5] offset:1024
	global_load_lds_dwordx4 v114, s[4:5] offset:2048
	global_load_lds_dwordx4 v115, s[4:5] offset:3072
	s_add_u32 m0, s98, 0x9000
	s_nop 0
	global_load_lds_dwordx4 v116, s[4:5] offset:0
	global_load_lds_dwordx4 v117, s[4:5] offset:1024
	global_load_lds_dwordx4 v118, s[4:5] offset:2048
	global_load_lds_dwordx4 v119, s[4:5] offset:3072
	s_add_u32 s4, s4, 0x80
	s_addc_u32 s5, s5, 0
	v_mov_b32_e32 v48, 0
	v_mov_b32_e32 v49, 0
	v_mov_b32_e32 v50, 0
	v_mov_b32_e32 v51, 0
	v_mov_b32_e32 v52, 0
	v_mov_b32_e32 v53, 0
	v_mov_b32_e32 v54, 0
	v_mov_b32_e32 v55, 0
	v_mov_b32_e32 v56, 0
	v_mov_b32_e32 v57, 0
	v_mov_b32_e32 v58, 0
	v_mov_b32_e32 v59, 0
	v_mov_b32_e32 v60, 0
	v_mov_b32_e32 v61, 0
	v_mov_b32_e32 v62, 0
	v_mov_b32_e32 v63, 0
	v_mov_b32_e32 v16, 0
	v_mov_b32_e32 v17, 0
	v_mov_b32_e32 v18, 0
	v_mov_b32_e32 v19, 0
	v_mov_b32_e32 v20, 0
	v_mov_b32_e32 v21, 0
	v_mov_b32_e32 v22, 0
	v_mov_b32_e32 v23, 0
	v_mov_b32_e32 v24, 0
	v_mov_b32_e32 v25, 0
	v_mov_b32_e32 v26, 0
	v_mov_b32_e32 v27, 0
	v_mov_b32_e32 v28, 0
	v_mov_b32_e32 v29, 0
	v_mov_b32_e32 v30, 0
	v_mov_b32_e32 v31, 0
	v_mov_b32_e32 v32, 0
	v_mov_b32_e32 v33, 0
	v_mov_b32_e32 v34, 0
	v_mov_b32_e32 v35, 0
	v_mov_b32_e32 v36, 0
	v_mov_b32_e32 v37, 0
	v_mov_b32_e32 v38, 0
	v_mov_b32_e32 v39, 0
	v_mov_b32_e32 v40, 0
	v_mov_b32_e32 v41, 0
	v_mov_b32_e32 v42, 0
	v_mov_b32_e32 v43, 0
	v_mov_b32_e32 v44, 0
	v_mov_b32_e32 v45, 0
	v_mov_b32_e32 v46, 0
	v_mov_b32_e32 v47, 0
	v_mov_b32_e32 v0, 0
	v_mov_b32_e32 v1, 0
	v_mov_b32_e32 v2, 0
	v_mov_b32_e32 v3, 0
	v_mov_b32_e32 v4, 0
	v_mov_b32_e32 v5, 0
	v_mov_b32_e32 v6, 0
	v_mov_b32_e32 v7, 0
	v_mov_b32_e32 v8, 0
	v_mov_b32_e32 v9, 0
	v_mov_b32_e32 v10, 0
	v_mov_b32_e32 v11, 0
	v_mov_b32_e32 v12, 0
	v_mov_b32_e32 v13, 0
	v_mov_b32_e32 v14, 0
	v_mov_b32_e32 v15, 0
	s_lshr_b32 s7, s8, 1
	s_sub_u32 s7, s7, 1
	s_waitcnt vmcnt(8)
.Lg5_loop:
	s_waitcnt vmcnt(8)
	s_barrier
	ds_read_b128 v[64:67], v120 offset:0
	ds_read_b128 v[72:75], v124 offset:0
	ds_read_b128 v[76:79], v124 offset:4096
	ds_read_b128 v[68:71], v120 offset:4096
	ds_read_b128 v[80:83], v121 offset:0
	ds_read_b128 v[88:91], v125 offset:0
	ds_read_b128 v[92:95], v125 offset:4096
	ds_read_b128 v[84:87], v121 offset:4096
	s_waitcnt lgkmcnt(4)
	v_mfma_f32_32x32x16_bf16 v[48:63], v[64:67], v[72:75], v[48:63]
	ds_read_b128 v[96:99], v122 offset:0
	v_mfma_f32_32x32x16_bf16 v[16:31], v[64:67], v[76:79], v[16:31]
	ds_read_b128 v[104:107], v126 offset:0
	v_mfma_f32_32x32x16_bf16 v[32:47], v[68:71], v[72:75], v[32:47]
	ds_read_b128 v[108:111], v126 offset:4096
	v_mfma_f32_32x32x16_bf16 v[0:15], v[68:71], v[76:79], v[0:15]
	ds_read_b128 v[100:103], v122 offset:4096
	s_waitcnt lgkmcnt(4)
	v_mfma_f32_32x32x16_bf16 v[48:63], v[80:83], v[88:91], v[48:63]
	ds_read_b128 v[64:67], v123 offset:0
	v_mfma_f32_32x32x16_bf16 v[16:31], v[80:83], v[92:95], v[16:31]
	ds_read_b128 v[72:75], v127 offset:0
	v_mfma_f32_32x32x16_bf16 v[32:47], v[84:87], v[88:91], v[32:47]
	ds_read_b128 v[76:79], v127 offset:4096
	v_mfma_f32_32x32x16_bf16 v[0:15], v[84:87], v[92:95], v[0:15]
	ds_read_b128 v[68:71], v123 offset:4096
	s_waitcnt lgkmcnt(4)
	v_mfma_f32_32x32x16_bf16 v[48:63], v[96:99], v[104:107], v[48:63]
	v_mfma_f32_32x32x16_bf16 v[16:31], v[96:99], v[108:111], v[16:31]
	v_mfma_f32_32x32x16_bf16 v[32:47], v[100:103], v[104:107], v[32:47]
	v_mfma_f32_32x32x16_bf16 v[0:15], v[100:103], v[108:111], v[0:15]
	s_waitcnt lgkmcnt(0)
	v_mfma_f32_32x32x16_bf16 v[48:63], v[64:67], v[72:75], v[48:63]
	v_mfma_f32_32x32x16_bf16 v[16:31], v[64:67], v[76:79], v[16:31]
	v_mfma_f32_32x32x16_bf16 v[32:47], v[68:71], v[72:75], v[32:47]
	v_mfma_f32_32x32x16_bf16 v[0:15], v[68:71], v[76:79], v[0:15]
	s_barrier
	s_add_u32 m0, s98, 0x0
	s_nop 0
	global_load_lds_dwordx4 v112, s[4:5] offset:0
	global_load_lds_dwordx4 v113, s[4:5] offset:1024
	global_load_lds_dwordx4 v114, s[4:5] offset:2048
	global_load_lds_dwordx4 v115, s[4:5] offset:3072
	s_add_u32 m0, s98, 0x1000
	s_nop 0
	global_load_lds_dwordx4 v116, s[4:5] offset:0
	global_load_lds_dwordx4 v117, s[4:5] offset:1024
	global_load_lds_dwordx4 v118, s[4:5] offset:2048
	global_load_lds_dwordx4 v119, s[4:5] offset:3072
	s_add_u32 s4, s4, 0x80
	s_addc_u32 s5, s5, 0
	s_waitcnt vmcnt(8)
	s_barrier
	ds_read_b128 v[64:67], v120 offset:32768
	ds_read_b128 v[72:75], v124 offset:32768
	ds_read_b128 v[76:79], v124 offset:36864
	ds_read_b128 v[68:71], v120 offset:36864
	ds_read_b128 v[80:83], v121 offset:32768
	ds_read_b128 v[88:91], v125 offset:32768
	ds_read_b128 v[92:95], v125 offset:36864
	ds_read_b128 v[84:87], v121 offset:36864
	s_waitcnt lgkmcnt(4)
	v_mfma_f32_32x32x16_bf16 v[48:63], v[64:67], v[72:75], v[48:63]
	ds_read_b128 v[96:99], v122 offset:32768
	v_mfma_f32_32x32x16_bf16 v[16:31], v[64:67], v[76:79], v[16:31]
	ds_read_b128 v[104:107], v126 offset:32768
	v_mfma_f32_32x32x16_bf16 v[32:47], v[68:71], v[72:75], v[32:47]
	ds_read_b128 v[108:111], v126 offset:36864
	v_mfma_f32_32x32x16_bf16 v[0:15], v[68:71], v[76:79], v[0:15]
	ds_read_b128 v[100:103], v122 offset:36864
	s_waitcnt lgkmcnt(4)
	v_mfma_f32_32x32x16_bf16 v[48:63], v[80:83], v[88:91], v[48:63]
	ds_read_b128 v[64:67], v123 offset:32768
	v_mfma_f32_32x32x16_bf16 v[16:31], v[80:83], v[92:95], v[16:31]
	ds_read_b128 v[72:75], v127 offset:32768
	v_mfma_f32_32x32x16_bf16 v[32:47], v[84:87], v[88:91], v[32:47]
	ds_read_b128 v[76:79], v127 offset:36864
	v_mfma_f32_32x32x16_bf16 v[0:15], v[84:87], v[92:95], v[0:15]
	ds_read_b128 v[68:71], v123 offset:36864
	s_waitcnt lgkmcnt(4)
	v_mfma_f32_32x32x16_bf16 v[48:63], v[96:99], v[104:107], v[48:63]
	v_mfma_f32_32x32x16_bf16 v[16:31], v[96:99], v[108:111], v[16:31]
	v_mfma_f32_32x32x16_bf16 v[32:47], v[100:103], v[104:107], v[32:47]
	v_mfma_f32_32x32x16_bf16 v[0:15], v[100:103], v[108:111], v[0:15]
	s_waitcnt lgkmcnt(0)
	v_mfma_f32_32x32x16_bf16 v[48:63], v[64:67], v[72:75], v[48:63]
	v_mfma_f32_32x32x16_bf16 v[16:31], v[64:67], v[76:79], v[16:31]
	v_mfma_f32_32x32x16_bf16 v[32:47], v[68:71], v[72:75], v[32:47]
	v_mfma_f32_32x32x16_bf16 v[0:15], v[68:71], v[76:79], v[0:15]
	s_barrier
	s_add_u32 m0, s98, 0x8000
	s_nop 0
	global_load_lds_dwordx4 v112, s[4:5] offset:0
	global_load_lds_dwordx4 v113, s[4:5] offset:1024
	global_load_lds_dwordx4 v114, s[4:5] offset:2048
	global_load_lds_dwordx4 v115, s[4:5] offset:3072
	s_add_u32 m0, s98, 0x9000
	s_nop 0
	global_load_lds_dwordx4 v116, s[4:5] offset:0
	global_load_lds_dwordx4 v117, s[4:5] offset:1024
	global_load_lds_dwordx4 v118, s[4:5] offset:2048
	global_load_lds_dwordx4 v119, s[4:5] offset:3072
	s_add_u32 s4, s4, 0x80
	s_addc_u32 s5, s5, 0
	s_sub_u32 s7, s7, 1
	s_cmp_lg_u32 s7, 0
	s_cbranch_scc1 .Lg5_loop
	s_waitcnt vmcnt(8)
	s_barrier
	ds_read_b128 v[64:67], v120 offset:0
	ds_read_b128 v[72:75], v124 offset:0
	ds_read_b128 v[76:79], v124 offset:4096
	ds_read_b128 v[68:71], v120 offset:4096
	ds_read_b128 v[80:83], v121 offset:0
	ds_read_b128 v[88:91], v125 offset:0
	ds_read_b128 v[92:95], v125 offset:4096
	ds_read_b128 v[84:87], v121 offset:4096
	s_waitcnt lgkmcnt(4)
	v_mfma_f32_32x32x16_bf16 v[48:63], v[64:67], v[72:75], v[48:63]
	ds_read_b128 v[96:99], v122 offset:0
	v_mfma_f32_32x32x16_bf16 v[16:31], v[64:67], v[76:79], v[16:31]
	ds_read_b128 v[104:107], v126 offset:0
	v_mfma_f32_32x32x16_bf16 v[32:47], v[68:71], v[72:75], v[32:47]
	ds_read_b128 v[108:111], v126 offset:4096
	v_mfma_f32_32x32x16_bf16 v[0:15], v[68:71], v[76:79], v[0:15]
	ds_read_b128 v[100:103], v122 offset:4096
	s_waitcnt lgkmcnt(4)
	v_mfma_f32_32x32x16_bf16 v[48:63], v[80:83], v[88:91], v[48:63]
	ds_read_b128 v[64:67], v123 offset:0
	v_mfma_f32_32x32x16_bf16 v[16:31], v[80:83], v[92:95], v[16:31]
	ds_read_b128 v[72:75], v127 offset:0
	v_mfma_f32_32x32x16_bf16 v[32:47], v[84:87], v[88:91], v[32:47]
	ds_read_b128 v[76:79], v127 offset:4096
	v_mfma_f32_32x32x16_bf16 v[0:15], v[84:87], v[92:95], v[0:15]
	ds_read_b128 v[68:71], v123 offset:4096
	s_waitcnt lgkmcnt(4)
	v_mfma_f32_32x32x16_bf16 v[48:63], v[96:99], v[104:107], v[48:63]
	v_mfma_f32_32x32x16_bf16 v[16:31], v[96:99], v[108:111], v[16:31]
	v_mfma_f32_32x32x16_bf16 v[32:47], v[100:103], v[104:107], v[32:47]
	v_mfma_f32_32x32x16_bf16 v[0:15], v[100:103], v[108:111], v[0:15]
	s_waitcnt lgkmcnt(0)
	v_mfma_f32_32x32x16_bf16 v[48:63], v[64:67], v[72:75], v[48:63]
	v_mfma_f32_32x32x16_bf16 v[16:31], v[64:67], v[76:79], v[16:31]
	v_mfma_f32_32x32x16_bf16 v[32:47], v[68:71], v[72:75], v[32:47]
	v_mfma_f32_32x32x16_bf16 v[0:15], v[68:71], v[76:79], v[0:15]
	s_barrier
	s_waitcnt vmcnt(0)
	s_barrier
	ds_read_b128 v[64:67], v120 offset:32768
	ds_read_b128 v[72:75], v124 offset:32768
	ds_read_b128 v[76:79], v124 offset:36864
	ds_read_b128 v[68:71], v120 offset:36864
	ds_read_b128 v[80:83], v121 offset:32768
	ds_read_b128 v[88:91], v125 offset:32768
	ds_read_b128 v[92:95], v125 offset:36864
	ds_read_b128 v[84:87], v121 offset:36864
	s_waitcnt lgkmcnt(4)
	v_mfma_f32_32x32x16_bf16 v[48:63], v[64:67], v[72:75], v[48:63]
	ds_read_b128 v[96:99], v122 offset:32768
	v_mfma_f32_32x32x16_bf16 v[16:31], v[64:67], v[76:79], v[16:31]
	ds_read_b128 v[104:107], v126 offset:32768
	v_mfma_f32_32x32x16_bf16 v[32:47], v[68:71], v[72:75], v[32:47]
	ds_read_b128 v[108:111], v126 offset:36864
	v_mfma_f32_32x32x16_bf16 v[0:15], v[68:71], v[76:79], v[0:15]
	ds_read_b128 v[100:103], v122 offset:36864
	s_waitcnt lgkmcnt(4)
	v_mfma_f32_32x32x16_bf16 v[48:63], v[80:83], v[88:91], v[48:63]
	ds_read_b128 v[64:67], v123 offset:32768
	v_mfma_f32_32x32x16_bf16 v[16:31], v[80:83], v[92:95], v[16:31]
	ds_read_b128 v[72:75], v127 offset:32768
	v_mfma_f32_32x32x16_bf16 v[32:47], v[84:87], v[88:91], v[32:47]
	ds_read_b128 v[76:79], v127 offset:36864
	v_mfma_f32_32x32x16_bf16 v[0:15], v[84:87], v[92:95], v[0:15]
	ds_read_b128 v[68:71], v123 offset:36864
	s_waitcnt lgkmcnt(4)
	v_mfma_f32_32x32x16_bf16 v[48:63], v[96:99], v[104:107], v[48:63]
	v_mfma_f32_32x32x16_bf16 v[16:31], v[96:99], v[108:111], v[16:31]
	v_mfma_f32_32x32x16_bf16 v[32:47], v[100:103], v[104:107], v[32:47]
	v_mfma_f32_32x32x16_bf16 v[0:15], v[100:103], v[108:111], v[0:15]
	s_waitcnt lgkmcnt(0)
	v_mfma_f32_32x32x16_bf16 v[48:63], v[64:67], v[72:75], v[48:63]
	v_mfma_f32_32x32x16_bf16 v[16:31], v[64:67], v[76:79], v[16:31]
	v_mfma_f32_32x32x16_bf16 v[32:47], v[68:71], v[72:75], v[32:47]
	v_mfma_f32_32x32x16_bf16 v[0:15], v[68:71], v[76:79], v[0:15]
	s_nop 7
	s_nop 7
	s_branch .LBB0_1882

.LBB0_2348:
	s_cmp_ge_i32 s33, s72
	s_cselect_b64 s[26:27], -1, 0
	s_sub_i32 s2, s33, s72
	s_and_b32 s3, 1, s2
	s_lshr_b32 s2, s2, 1
	s_add_i32 s2, s2, s72
	s_cmp_eq_u32 s3, 1
	s_cselect_b32 s3, 0x580, 0
	s_cmp_lt_i32 s33, s72
	s_cselect_b32 s2, s33, s2
	s_mul_hi_i32 s4, s2, 0x2aaaaaab
	s_cselect_b32 s6, 44, 22
	s_cselect_b32 s3, 0, s3
	s_lshr_b32 s5, s4, 31
	s_ashr_i32 s4, s4, 4
	s_add_i32 s4, s4, s5
	s_mul_i32 s5, s4, 0x60
	s_sub_i32 s2, s2, s5
	s_lshl_b32 s7, s2, 7
	s_lshl_b32 s18, s3, 1
	s_lshl_b32 s8, s4, 7
	v_lshl_or_b32 v64, v183, 3, v191
	v_and_b32_e32 v65, 63, v64
	v_lshrrev_b32_e32 v66, 3, v65
	v_lshrrev_b32_e32 v67, 4, v65
	v_xor_b32_e32 v67, v67, v65
	v_and_b32_e32 v67, 7, v67
	v_lshlrev_b32_e32 v67, 4, v67
	s_movk_i32 s99, 0x1600
	v_mad_u32_u24 v112, v66, s99, v67
	v_xor_b32_e32 v68, 64, v112
	v_add_u32_e32 v113, 0xac00, v68
	v_add_u32_e32 v114, 0x15800, v112
	v_add_u32_e32 v115, 0x20400, v68
	v_add_u32_e32 v116, 0x2c000, v112
	v_add_u32_e32 v117, 0x36c00, v68
	v_add_u32_e32 v118, 0x41800, v112
	v_add_u32_e32 v119, 0x4c400, v68
	v_and_b32_e32 v69, 31, v64
	v_bfe_u32 v70, v64, 5, 1
	v_bfe_u32 v71, v64, 1, 3
	v_xor_b32_e32 v71, v71, v70
	v_lshlrev_b32_e32 v71, 4, v71
	v_bfe_u32 v72, v64, 7, 1
	v_lshl_or_b32 v72, v72, 6, v69
	v_lshl_add_u32 v120, v72, 7, v71
	v_bfe_u32 v73, v64, 6, 1
	v_lshl_or_b32 v73, v73, 6, v69
	v_lshl_add_u32 v124, v73, 7, v71
	v_add_u32_e32 v124, 0x4000, v124
	v_xor_b32_e32 v121, 32, v120
	v_xor_b32_e32 v125, 32, v124
	v_xor_b32_e32 v122, 64, v120
	v_xor_b32_e32 v126, 64, v124
	v_xor_b32_e32 v123, 96, v120
	v_xor_b32_e32 v127, 96, v124
	v_lshrrev_b32_e32 v74, 6, v64
	s_nop 0
	v_readfirstlane_b32 s100, v74
	s_nop 3
	s_lshl_b32 s98, s100, 13
	s_mov_b32 s101, 0x26c0000
	s_mov_b32 s99, s8
	s_cmp_lt_u32 s100, 2
	s_cmov_b32 s101, 0x3971900
	s_cmov_b32 s99, s7
	s_and_b32 s100, s100, 1
	s_lshl_b32 s100, s100, 6
	s_add_u32 s99, s99, s100
	s_mul_i32 s99, s99, 0x1600
	s_add_u32 s99, s99, s101
	s_add_u32 s99, s99, s18
	s_add_u32 s2, s90, s99
	s_addc_u32 s3, s91, 0
	s_add_u32 m0, s98, 0x0
	s_nop 0
	global_load_lds_dwordx4 v112, s[2:3] offset:0
	global_load_lds_dwordx4 v113, s[2:3] offset:1024
	global_load_lds_dwordx4 v114, s[2:3] offset:2048
	global_load_lds_dwordx4 v115, s[2:3] offset:3072
	s_add_u32 m0, s98, 0x1000
	s_nop 0
	global_load_lds_dwordx4 v116, s[2:3] offset:0
	global_load_lds_dwordx4 v117, s[2:3] offset:1024
	global_load_lds_dwordx4 v118, s[2:3] offset:2048
	global_load_lds_dwordx4 v119, s[2:3] offset:3072
	s_add_u32 s2, s2, 0x80
	s_addc_u32 s3, s3, 0
	s_add_u32 m0, s98, 0x8000
	s_nop 0
	global_load_lds_dwordx4 v112, s[2:3] offset:0
	global_load_lds_dwordx4 v113, s[2:3] offset:1024
	global_load_lds_dwordx4 v114, s[2:3] offset:2048
	global_load_lds_dwordx4 v115, s[2:3] offset:3072
	s_add_u32 m0, s98, 0x9000
	s_nop 0
	global_load_lds_dwordx4 v116, s[2:3] offset:0
	global_load_lds_dwordx4 v117, s[2:3] offset:1024
	global_load_lds_dwordx4 v118, s[2:3] offset:2048
	global_load_lds_dwordx4 v119, s[2:3] offset:3072
	s_add_u32 s2, s2, 0x80
	s_addc_u32 s3, s3, 0
	v_mov_b32_e32 v48, 0
	v_mov_b32_e32 v49, 0
	v_mov_b32_e32 v50, 0
	v_mov_b32_e32 v51, 0
	v_mov_b32_e32 v52, 0
	v_mov_b32_e32 v53, 0
	v_mov_b32_e32 v54, 0
	v_mov_b32_e32 v55, 0
	v_mov_b32_e32 v56, 0
	v_mov_b32_e32 v57, 0
	v_mov_b32_e32 v58, 0
	v_mov_b32_e32 v59, 0
	v_mov_b32_e32 v60, 0
	v_mov_b32_e32 v61, 0
	v_mov_b32_e32 v62, 0
	v_mov_b32_e32 v63, 0
	v_mov_b32_e32 v16, 0
	v_mov_b32_e32 v17, 0
	v_mov_b32_e32 v18, 0
	v_mov_b32_e32 v19, 0
	v_mov_b32_e32 v20, 0
	v_mov_b32_e32 v21, 0
	v_mov_b32_e32 v22, 0
	v_mov_b32_e32 v23, 0
	v_mov_b32_e32 v24, 0
	v_mov_b32_e32 v25, 0
	v_mov_b32_e32 v26, 0
	v_mov_b32_e32 v27, 0
	v_mov_b32_e32 v28, 0
	v_mov_b32_e32 v29, 0
	v_mov_b32_e32 v30, 0
	v_mov_b32_e32 v31, 0
	v_mov_b32_e32 v32, 0
	v_mov_b32_e32 v33, 0
	v_mov_b32_e32 v34, 0
	v_mov_b32_e32 v35, 0
	v_mov_b32_e32 v36, 0
	v_mov_b32_e32 v37, 0
	v_mov_b32_e32 v38, 0
	v_mov_b32_e32 v39, 0
	v_mov_b32_e32 v40, 0
	v_mov_b32_e32 v41, 0
	v_mov_b32_e32 v42, 0
	v_mov_b32_e32 v43, 0
	v_mov_b32_e32 v44, 0
	v_mov_b32_e32 v45, 0
	v_mov_b32_e32 v46, 0
	v_mov_b32_e32 v47, 0
	v_mov_b32_e32 v0, 0
	v_mov_b32_e32 v1, 0
	v_mov_b32_e32 v2, 0
	v_mov_b32_e32 v3, 0
	v_mov_b32_e32 v4, 0
	v_mov_b32_e32 v5, 0
	v_mov_b32_e32 v6, 0
	v_mov_b32_e32 v7, 0
	v_mov_b32_e32 v8, 0
	v_mov_b32_e32 v9, 0
	v_mov_b32_e32 v10, 0
	v_mov_b32_e32 v11, 0
	v_mov_b32_e32 v12, 0
	v_mov_b32_e32 v13, 0
	v_mov_b32_e32 v14, 0
	v_mov_b32_e32 v15, 0
	s_lshr_b32 s5, s6, 1
	s_sub_u32 s5, s5, 1
	s_waitcnt vmcnt(8)
.Lg7_loop:
	s_waitcnt vmcnt(8)
	s_barrier
	ds_read_b128 v[64:67], v120 offset:0
	ds_read_b128 v[72:75], v124 offset:0
	ds_read_b128 v[76:79], v124 offset:4096
	ds_read_b128 v[68:71], v120 offset:4096
	ds_read_b128 v[80:83], v121 offset:0
	ds_read_b128 v[88:91], v125 offset:0
	ds_read_b128 v[92:95], v125 offset:4096
	ds_read_b128 v[84:87], v121 offset:4096
	s_waitcnt lgkmcnt(4)
	v_mfma_f32_32x32x16_bf16 v[48:63], v[64:67], v[72:75], v[48:63]
	ds_read_b128 v[96:99], v122 offset:0
	v_mfma_f32_32x32x16_bf16 v[16:31], v[64:67], v[76:79], v[16:31]
	ds_read_b128 v[104:107], v126 offset:0
	v_mfma_f32_32x32x16_bf16 v[32:47], v[68:71], v[72:75], v[32:47]
	ds_read_b128 v[108:111], v126 offset:4096
	v_mfma_f32_32x32x16_bf16 v[0:15], v[68:71], v[76:79], v[0:15]
	ds_read_b128 v[100:103], v122 offset:4096
	s_waitcnt lgkmcnt(4)
	v_mfma_f32_32x32x16_bf16 v[48:63], v[80:83], v[88:91], v[48:63]
	ds_read_b128 v[64:67], v123 offset:0
	v_mfma_f32_32x32x16_bf16 v[16:31], v[80:83], v[92:95], v[16:31]
	ds_read_b128 v[72:75], v127 offset:0
	v_mfma_f32_32x32x16_bf16 v[32:47], v[84:87], v[88:91], v[32:47]
	ds_read_b128 v[76:79], v127 offset:4096
	v_mfma_f32_32x32x16_bf16 v[0:15], v[84:87], v[92:95], v[0:15]
	ds_read_b128 v[68:71], v123 offset:4096
	s_waitcnt lgkmcnt(4)
	v_mfma_f32_32x32x16_bf16 v[48:63], v[96:99], v[104:107], v[48:63]
	v_mfma_f32_32x32x16_bf16 v[16:31], v[96:99], v[108:111], v[16:31]
	v_mfma_f32_32x32x16_bf16 v[32:47], v[100:103], v[104:107], v[32:47]
	v_mfma_f32_32x32x16_bf16 v[0:15], v[100:103], v[108:111], v[0:15]
	s_waitcnt lgkmcnt(0)
	v_mfma_f32_32x32x16_bf16 v[48:63], v[64:67], v[72:75], v[48:63]
	v_mfma_f32_32x32x16_bf16 v[16:31], v[64:67], v[76:79], v[16:31]
	v_mfma_f32_32x32x16_bf16 v[32:47], v[68:71], v[72:75], v[32:47]
	v_mfma_f32_32x32x16_bf16 v[0:15], v[68:71], v[76:79], v[0:15]
	s_barrier
	s_add_u32 m0, s98, 0x0
	s_nop 0
	global_load_lds_dwordx4 v112, s[2:3] offset:0
	global_load_lds_dwordx4 v113, s[2:3] offset:1024
	global_load_lds_dwordx4 v114, s[2:3] offset:2048
	global_load_lds_dwordx4 v115, s[2:3] offset:3072
	s_add_u32 m0, s98, 0x1000
	s_nop 0
	global_load_lds_dwordx4 v116, s[2:3] offset:0
	global_load_lds_dwordx4 v117, s[2:3] offset:1024
	global_load_lds_dwordx4 v118, s[2:3] offset:2048
	global_load_lds_dwordx4 v119, s[2:3] offset:3072
	s_add_u32 s2, s2, 0x80
	s_addc_u32 s3, s3, 0
	s_waitcnt vmcnt(8)
	s_barrier
	ds_read_b128 v[64:67], v120 offset:32768
	ds_read_b128 v[72:75], v124 offset:32768
	ds_read_b128 v[76:79], v124 offset:36864
	ds_read_b128 v[68:71], v120 offset:36864
	ds_read_b128 v[80:83], v121 offset:32768
	ds_read_b128 v[88:91], v125 offset:32768
	ds_read_b128 v[92:95], v125 offset:36864
	ds_read_b128 v[84:87], v121 offset:36864
	s_waitcnt lgkmcnt(4)
	v_mfma_f32_32x32x16_bf16 v[48:63], v[64:67], v[72:75], v[48:63]
	ds_read_b128 v[96:99], v122 offset:32768
	v_mfma_f32_32x32x16_bf16 v[16:31], v[64:67], v[76:79], v[16:31]
	ds_read_b128 v[104:107], v126 offset:32768
	v_mfma_f32_32x32x16_bf16 v[32:47], v[68:71], v[72:75], v[32:47]
	ds_read_b128 v[108:111], v126 offset:36864
	v_mfma_f32_32x32x16_bf16 v[0:15], v[68:71], v[76:79], v[0:15]
	ds_read_b128 v[100:103], v122 offset:36864
	s_waitcnt lgkmcnt(4)
	v_mfma_f32_32x32x16_bf16 v[48:63], v[80:83], v[88:91], v[48:63]
	ds_read_b128 v[64:67], v123 offset:32768
	v_mfma_f32_32x32x16_bf16 v[16:31], v[80:83], v[92:95], v[16:31]
	ds_read_b128 v[72:75], v127 offset:32768
	v_mfma_f32_32x32x16_bf16 v[32:47], v[84:87], v[88:91], v[32:47]
	ds_read_b128 v[76:79], v127 offset:36864
	v_mfma_f32_32x32x16_bf16 v[0:15], v[84:87], v[92:95], v[0:15]
	ds_read_b128 v[68:71], v123 offset:36864
	s_waitcnt lgkmcnt(4)
	v_mfma_f32_32x32x16_bf16 v[48:63], v[96:99], v[104:107], v[48:63]
	v_mfma_f32_32x32x16_bf16 v[16:31], v[96:99], v[108:111], v[16:31]
	v_mfma_f32_32x32x16_bf16 v[32:47], v[100:103], v[104:107], v[32:47]
	v_mfma_f32_32x32x16_bf16 v[0:15], v[100:103], v[108:111], v[0:15]
	s_waitcnt lgkmcnt(0)
	v_mfma_f32_32x32x16_bf16 v[48:63], v[64:67], v[72:75], v[48:63]
	v_mfma_f32_32x32x16_bf16 v[16:31], v[64:67], v[76:79], v[16:31]
	v_mfma_f32_32x32x16_bf16 v[32:47], v[68:71], v[72:75], v[32:47]
	v_mfma_f32_32x32x16_bf16 v[0:15], v[68:71], v[76:79], v[0:15]
	s_barrier
	s_add_u32 m0, s98, 0x8000
	s_nop 0
	global_load_lds_dwordx4 v112, s[2:3] offset:0
	global_load_lds_dwordx4 v113, s[2:3] offset:1024
	global_load_lds_dwordx4 v114, s[2:3] offset:2048
	global_load_lds_dwordx4 v115, s[2:3] offset:3072
	s_add_u32 m0, s98, 0x9000
	s_nop 0
	global_load_lds_dwordx4 v116, s[2:3] offset:0
	global_load_lds_dwordx4 v117, s[2:3] offset:1024
	global_load_lds_dwordx4 v118, s[2:3] offset:2048
	global_load_lds_dwordx4 v119, s[2:3] offset:3072
	s_add_u32 s2, s2, 0x80
	s_addc_u32 s3, s3, 0
	s_sub_u32 s5, s5, 1
	s_cmp_lg_u32 s5, 0
	s_cbranch_scc1 .Lg7_loop
	s_waitcnt vmcnt(8)
	s_barrier
	ds_read_b128 v[64:67], v120 offset:0
	ds_read_b128 v[72:75], v124 offset:0
	ds_read_b128 v[76:79], v124 offset:4096
	ds_read_b128 v[68:71], v120 offset:4096
	ds_read_b128 v[80:83], v121 offset:0
	ds_read_b128 v[88:91], v125 offset:0
	ds_read_b128 v[92:95], v125 offset:4096
	ds_read_b128 v[84:87], v121 offset:4096
	s_waitcnt lgkmcnt(4)
	v_mfma_f32_32x32x16_bf16 v[48:63], v[64:67], v[72:75], v[48:63]
	ds_read_b128 v[96:99], v122 offset:0
	v_mfma_f32_32x32x16_bf16 v[16:31], v[64:67], v[76:79], v[16:31]
	ds_read_b128 v[104:107], v126 offset:0
	v_mfma_f32_32x32x16_bf16 v[32:47], v[68:71], v[72:75], v[32:47]
	ds_read_b128 v[108:111], v126 offset:4096
	v_mfma_f32_32x32x16_bf16 v[0:15], v[68:71], v[76:79], v[0:15]
	ds_read_b128 v[100:103], v122 offset:4096
	s_waitcnt lgkmcnt(4)
	v_mfma_f32_32x32x16_bf16 v[48:63], v[80:83], v[88:91], v[48:63]
	ds_read_b128 v[64:67], v123 offset:0
	v_mfma_f32_32x32x16_bf16 v[16:31], v[80:83], v[92:95], v[16:31]
	ds_read_b128 v[72:75], v127 offset:0
	v_mfma_f32_32x32x16_bf16 v[32:47], v[84:87], v[88:91], v[32:47]
	ds_read_b128 v[76:79], v127 offset:4096
	v_mfma_f32_32x32x16_bf16 v[0:15], v[84:87], v[92:95], v[0:15]
	ds_read_b128 v[68:71], v123 offset:4096
	s_waitcnt lgkmcnt(4)
	v_mfma_f32_32x32x16_bf16 v[48:63], v[96:99], v[104:107], v[48:63]
	v_mfma_f32_32x32x16_bf16 v[16:31], v[96:99], v[108:111], v[16:31]
	v_mfma_f32_32x32x16_bf16 v[32:47], v[100:103], v[104:107], v[32:47]
	v_mfma_f32_32x32x16_bf16 v[0:15], v[100:103], v[108:111], v[0:15]
	s_waitcnt lgkmcnt(0)
	v_mfma_f32_32x32x16_bf16 v[48:63], v[64:67], v[72:75], v[48:63]
	v_mfma_f32_32x32x16_bf16 v[16:31], v[64:67], v[76:79], v[16:31]
	v_mfma_f32_32x32x16_bf16 v[32:47], v[68:71], v[72:75], v[32:47]
	v_mfma_f32_32x32x16_bf16 v[0:15], v[68:71], v[76:79], v[0:15]
	s_barrier
	s_waitcnt vmcnt(0)
	s_barrier
	ds_read_b128 v[64:67], v120 offset:32768
	ds_read_b128 v[72:75], v124 offset:32768
	ds_read_b128 v[76:79], v124 offset:36864
	ds_read_b128 v[68:71], v120 offset:36864
	ds_read_b128 v[80:83], v121 offset:32768
	ds_read_b128 v[88:91], v125 offset:32768
	ds_read_b128 v[92:95], v125 offset:36864
	ds_read_b128 v[84:87], v121 offset:36864
	s_waitcnt lgkmcnt(4)
	v_mfma_f32_32x32x16_bf16 v[48:63], v[64:67], v[72:75], v[48:63]
	ds_read_b128 v[96:99], v122 offset:32768
	v_mfma_f32_32x32x16_bf16 v[16:31], v[64:67], v[76:79], v[16:31]
	ds_read_b128 v[104:107], v126 offset:32768
	v_mfma_f32_32x32x16_bf16 v[32:47], v[68:71], v[72:75], v[32:47]
	ds_read_b128 v[108:111], v126 offset:36864
	v_mfma_f32_32x32x16_bf16 v[0:15], v[68:71], v[76:79], v[0:15]
	ds_read_b128 v[100:103], v122 offset:36864
	s_waitcnt lgkmcnt(4)
	v_mfma_f32_32x32x16_bf16 v[48:63], v[80:83], v[88:91], v[48:63]
	ds_read_b128 v[64:67], v123 offset:32768
	v_mfma_f32_32x32x16_bf16 v[16:31], v[80:83], v[92:95], v[16:31]
	ds_read_b128 v[72:75], v127 offset:32768
	v_mfma_f32_32x32x16_bf16 v[32:47], v[84:87], v[88:91], v[32:47]
	ds_read_b128 v[76:79], v127 offset:36864
	v_mfma_f32_32x32x16_bf16 v[0:15], v[84:87], v[92:95], v[0:15]
	ds_read_b128 v[68:71], v123 offset:36864
	s_waitcnt lgkmcnt(4)
	v_mfma_f32_32x32x16_bf16 v[48:63], v[96:99], v[104:107], v[48:63]
	v_mfma_f32_32x32x16_bf16 v[16:31], v[96:99], v[108:111], v[16:31]
	v_mfma_f32_32x32x16_bf16 v[32:47], v[100:103], v[104:107], v[32:47]
	v_mfma_f32_32x32x16_bf16 v[0:15], v[100:103], v[108:111], v[0:15]
	s_waitcnt lgkmcnt(0)
	v_mfma_f32_32x32x16_bf16 v[48:63], v[64:67], v[72:75], v[48:63]
	v_mfma_f32_32x32x16_bf16 v[16:31], v[64:67], v[76:79], v[16:31]
	v_mfma_f32_32x32x16_bf16 v[32:47], v[68:71], v[72:75], v[32:47]
	v_mfma_f32_32x32x16_bf16 v[0:15], v[68:71], v[76:79], v[0:15]
	s_nop 7
	s_nop 7
	s_branch .LBB0_2356
